# up-GEMM conv epilogue (second half, interior path): each group's 6 LDS reads issued one group ahead into rotating free register sets
# speedup vs baseline: 1.0021x; 1.0021x over previous
;     __device__ __forceinline__ void run(f32x4 (&acc)[2][2][4][2], const Unit& u, int wr, int wc, int fr_, int fq_, int par) const {
;     ...
;         for (int ai = 0; ai < 2; ++ai)
; #pragma unroll
;             for (int m = 0; m < 4; ++m) { const float sc = rsl[ai * HALF + wr * 64 + 4 * fr + m];
; #pragma unroll
;                 for (int bj = 0; bj < 2; ++bj)
; #pragma unroll
;                     for (int n = 0; n < 2; ++n) acc[ai][bj][m][n] = acc[ai][bj][m][n] * sc; }
;     ...
;         for (int ai = 0; ai < 2; ++ai) {
;             const bool has_prev = (wr | ai) != 0;
;             const int swr = wr ^ 1, sai = wr ? ai : 0;
;             const int growu = a_row0 + u.pm * a_rstep + ai * HALF + wr * 64;
;             const int grow0 = growu + 4 * fr;
;             const int tz = ((grow0 % seqlen) + seqlen) % seqlen;
.LBB0_605:
	s_or_b64 exec, exec, s[4:5]
	v_lshl_add_u32 v133, v250, 4, v247
	ds_read_b128 v[154:157], v133
	ds_read_b128 v[158:161], v133 offset:256
	ds_read_b128 v[162:165], v249
	ds_read_b128 v[168:171], v249 offset:1024
	ds_read_b128 v[172:175], v249 offset:2048
	ds_read_b128 v[176:179], v249 offset:3072
	v_pk_mul_f32 v[122:123], v[34:35], v[66:67] op_sel_hi:[1,0]
	v_pk_mul_f32 v[124:125], v[36:37], v[66:67] op_sel_hi:[1,0]
	v_pk_mul_f32 v[114:115], v[30:31], v[66:67] op_sel_hi:[1,0]
	v_pk_mul_f32 v[116:117], v[32:33], v[66:67] op_sel_hi:[1,0]
	v_pk_mul_f32 v[106:107], v[14:15], v[66:67] op_sel_hi:[1,0]
	v_pk_mul_f32 v[108:109], v[16:17], v[66:67] op_sel_hi:[1,0]
	v_pk_mul_f32 v[98:99], v[10:11], v[66:67] op_sel_hi:[1,0]
	v_pk_mul_f32 v[100:101], v[12:13], v[66:67] op_sel_hi:[1,0]
	v_pk_mul_f32 v[126:127], v[22:23], v[66:67] op_sel:[0,1]
	v_pk_mul_f32 v[128:129], v[24:25], v[66:67] op_sel:[0,1]
	v_pk_mul_f32 v[118:119], v[18:19], v[66:67] op_sel:[0,1]
	v_pk_mul_f32 v[120:121], v[20:21], v[66:67] op_sel:[0,1]
	v_pk_mul_f32 v[110:111], v[6:7], v[66:67] op_sel:[0,1]
	v_pk_mul_f32 v[112:113], v[8:9], v[66:67] op_sel:[0,1]
	v_pk_mul_f32 v[102:103], v[2:3], v[66:67] op_sel:[0,1]
	v_pk_mul_f32 v[104:105], v[4:5], v[66:67] op_sel:[0,1]
	s_add_i32 s14, s43, s14
	v_add_u32_e32 v132, s14, v251
	v_mul_hi_i32 v2, v132, s62
	v_lshrrev_b32_e32 v3, 31, v2
	v_ashrrev_i32_e32 v2, 7, v2
	v_add_u32_e32 v2, v2, v3
	s_movk_i32 s4, 0x810
	v_mul_lo_u32 v2, v2, s4
	v_sub_u32_e32 v2, v132, v2
	v_add_u32_e32 v3, 0x810, v2
	v_cmp_gt_i32_e32 vcc, 0, v2
	s_movk_i32 s4, 0xf7f5
	v_cndmask_b32_e32 v2, v2, v3, vcc
	v_add_u32_e32 v3, 0xfffff7f3, v2
	v_cmp_gt_u32_e32 vcc, s4, v3
	s_cbranch_vccz .LBB0_623
	s_waitcnt lgkmcnt(0)
	ds_read_b128 v[180:183], v133 offset:64
	ds_read_b128 v[184:187], v133 offset:320
	ds_read_b128 v[188:191], v249 offset:16
	ds_read_b128 v[192:195], v249 offset:1040
	ds_read_b128 v[196:199], v249 offset:2064
	ds_read_b128 v[208:211], v249 offset:3088
	v_mov_b32_dpp v156, v60 row_shr:1 row_mask:0xf bank_mask:0xf
	v_mov_b32_dpp v157, v61 row_shr:1 row_mask:0xf bank_mask:0xf
	v_cmp_eq_u32_e32 vcc, 0, v2
	v_mov_b32_dpp v154, v58 row_shr:1 row_mask:0xf bank_mask:0xf
	v_mov_b32_dpp v155, v59 row_shr:1 row_mask:0xf bank_mask:0xf
	v_mov_b32_dpp v160, v64 row_shr:1 row_mask:0xf bank_mask:0xf
	v_mov_b32_dpp v161, v65 row_shr:1 row_mask:0xf bank_mask:0xf
	v_cndmask_b32_e64 v157, v157, 0, vcc
	v_cndmask_b32_e64 v156, v156, 0, vcc
	v_mov_b32_dpp v158, v62 row_shr:1 row_mask:0xf bank_mask:0xf
	v_mov_b32_dpp v159, v63 row_shr:1 row_mask:0xf bank_mask:0xf
	v_cndmask_b32_e64 v161, v161, 0, vcc
	v_cndmask_b32_e64 v160, v160, 0, vcc
	v_cndmask_b32_e64 v155, v155, 0, vcc
	v_cndmask_b32_e64 v154, v154, 0, vcc
	v_pk_fma_f32 v[6:7], v[164:165], v[156:157], v[178:179]
	v_cndmask_b32_e64 v159, v159, 0, vcc
	v_cndmask_b32_e64 v158, v158, 0, vcc
	v_pk_fma_f32 v[4:5], v[162:163], v[154:155], v[176:177]
	v_pk_fma_f32 v[6:7], v[170:171], v[160:161], v[6:7]
	v_pk_fma_f32 v[4:5], v[168:169], v[158:159], v[4:5]
	v_pk_fma_f32 v[68:69], v[124:125], v[174:175], v[6:7]
	v_pk_fma_f32 v[6:7], v[162:163], v[158:159], v[176:177]
	s_movk_i32 s4, 0x80e
	v_pk_fma_f32 v[66:67], v[122:123], v[172:173], v[4:5]
	v_pk_fma_f32 v[4:5], v[164:165], v[160:161], v[178:179]
	v_pk_fma_f32 v[6:7], v[122:123], v[168:169], v[6:7]
	v_cmp_eq_u32_e64 s[4:5], s4, v2
	v_pk_fma_f32 v[4:5], v[124:125], v[170:171], v[4:5]
	v_pk_fma_f32 v[18:19], v[126:127], v[172:173], v[6:7]
	v_cndmask_b32_e64 v7, v123, 0, s[4:5]
	v_cndmask_b32_e64 v6, v122, 0, s[4:5]
	v_cndmask_b32_e64 v9, v125, 0, s[4:5]
	v_cndmask_b32_e64 v8, v124, 0, s[4:5]
	v_pk_fma_f32 v[20:21], v[128:129], v[174:175], v[4:5]
	v_cndmask_b32_e64 v3, v129, 0, s[4:5]
	v_cndmask_b32_e64 v2, v128, 0, s[4:5]
	v_cndmask_b32_e64 v5, v127, 0, s[4:5]
	v_cndmask_b32_e64 v4, v126, 0, s[4:5]
	v_pk_fma_f32 v[8:9], v[8:9], v[164:165], v[178:179]
	v_pk_fma_f32 v[6:7], v[6:7], v[162:163], v[176:177]
	v_pk_fma_f32 v[8:9], v[2:3], v[170:171], v[8:9]
	v_pk_fma_f32 v[6:7], v[4:5], v[168:169], v[6:7]
	v_pk_fma_f32 v[2:3], v[2:3], v[164:165], v[178:179]
	v_pk_fma_f32 v[4:5], v[4:5], v[162:163], v[176:177]
	v_pk_fma_f32 v[10:11], v[58:59], v[172:173], v[6:7]
	v_pk_fma_f32 v[6:7], v[58:59], v[168:169], v[4:5]
	v_pk_fma_f32 v[2:3], v[60:61], v[170:171], v[2:3]
	v_pk_fma_f32 v[12:13], v[60:61], v[174:175], v[8:9]
	v_pk_fma_f32 v[4:5], v[64:65], v[174:175], v[2:3]
	v_pk_fma_f32 v[2:3], v[62:63], v[172:173], v[6:7]
	s_waitcnt lgkmcnt(0)
	ds_read_b128 v[212:215], v133 offset:128
	ds_read_b128 v[216:219], v133 offset:384
	ds_read_b128 v[220:223], v249 offset:512
	ds_read_b128 v[224:227], v249 offset:1536
	ds_read_b128 v[228:231], v249 offset:2560
	ds_read_b128 v[232:235], v249 offset:3584
	v_mov_b32_dpp v180, v50 row_shr:1 row_mask:0xf bank_mask:0xf
	v_mov_b32_dpp v181, v51 row_shr:1 row_mask:0xf bank_mask:0xf
	v_mov_b32_dpp v182, v52 row_shr:1 row_mask:0xf bank_mask:0xf
	v_mov_b32_dpp v183, v53 row_shr:1 row_mask:0xf bank_mask:0xf
	v_mov_b32_dpp v184, v54 row_shr:1 row_mask:0xf bank_mask:0xf
	v_mov_b32_dpp v185, v55 row_shr:1 row_mask:0xf bank_mask:0xf
	v_mov_b32_dpp v186, v56 row_shr:1 row_mask:0xf bank_mask:0xf
	v_mov_b32_dpp v187, v57 row_shr:1 row_mask:0xf bank_mask:0xf
	v_cndmask_b32_e64 v181, v181, 0, vcc
	v_cndmask_b32_e64 v180, v180, 0, vcc
	v_cndmask_b32_e64 v183, v183, 0, vcc
	v_cndmask_b32_e64 v182, v182, 0, vcc
	v_cndmask_b32_e64 v187, v187, 0, vcc
	v_cndmask_b32_e64 v186, v186, 0, vcc
	v_cndmask_b32_e64 v185, v185, 0, vcc
	v_cndmask_b32_e64 v184, v184, 0, vcc
	v_pk_fma_f32 v[8:9], v[190:191], v[182:183], v[210:211]
	v_pk_fma_f32 v[6:7], v[188:189], v[180:181], v[208:209]
	v_pk_fma_f32 v[8:9], v[194:195], v[186:187], v[8:9]
	v_pk_fma_f32 v[6:7], v[192:193], v[184:185], v[6:7]
	v_pk_fma_f32 v[76:77], v[116:117], v[198:199], v[8:9]
	v_pk_fma_f32 v[74:75], v[114:115], v[196:197], v[6:7]
	v_pk_fma_f32 v[6:7], v[190:191], v[186:187], v[210:211]
	v_pk_fma_f32 v[8:9], v[188:189], v[184:185], v[208:209]
	v_pk_fma_f32 v[6:7], v[116:117], v[194:195], v[6:7]
	v_pk_fma_f32 v[8:9], v[114:115], v[192:193], v[8:9]
	v_cndmask_b32_e64 v15, v117, 0, s[4:5]
	v_cndmask_b32_e64 v14, v116, 0, s[4:5]
	v_cndmask_b32_e64 v17, v115, 0, s[4:5]
	v_cndmask_b32_e64 v16, v114, 0, s[4:5]
	v_pk_fma_f32 v[32:33], v[120:121], v[198:199], v[6:7]
	v_pk_fma_f32 v[30:31], v[118:119], v[196:197], v[8:9]
	v_cndmask_b32_e64 v7, v119, 0, s[4:5]
	v_cndmask_b32_e64 v6, v118, 0, s[4:5]
	v_cndmask_b32_e64 v9, v121, 0, s[4:5]
	v_cndmask_b32_e64 v8, v120, 0, s[4:5]
	v_pk_fma_f32 v[16:17], v[16:17], v[188:189], v[208:209]
	v_pk_fma_f32 v[14:15], v[14:15], v[190:191], v[210:211]
	s_nop 0
	v_pk_fma_f32 v[82:83], v[8:9], v[194:195], v[14:15]
	v_pk_fma_f32 v[14:15], v[6:7], v[192:193], v[16:17]
	v_pk_fma_f32 v[6:7], v[6:7], v[188:189], v[208:209]
	v_pk_fma_f32 v[8:9], v[8:9], v[190:191], v[210:211]
	v_pk_fma_f32 v[6:7], v[50:51], v[192:193], v[6:7]
	v_pk_fma_f32 v[8:9], v[52:53], v[194:195], v[8:9]
	v_pk_fma_f32 v[14:15], v[50:51], v[196:197], v[14:15]
	v_pk_fma_f32 v[16:17], v[52:53], v[198:199], v[82:83]
	v_pk_fma_f32 v[6:7], v[54:55], v[196:197], v[6:7]
	v_pk_fma_f32 v[8:9], v[56:57], v[198:199], v[8:9]
	s_waitcnt lgkmcnt(0)
	ds_read_b128 v[154:157], v133 offset:192
	ds_read_b128 v[158:161], v133 offset:448
	ds_read_b128 v[162:165], v249 offset:528
	ds_read_b128 v[168:171], v249 offset:1552
	ds_read_b128 v[172:175], v249 offset:2576
	ds_read_b128 v[176:179], v249 offset:3600
	v_mov_b32_dpp v212, v42 row_shr:1 row_mask:0xf bank_mask:0xf
	v_mov_b32_dpp v213, v43 row_shr:1 row_mask:0xf bank_mask:0xf
	v_mov_b32_dpp v214, v44 row_shr:1 row_mask:0xf bank_mask:0xf
	v_mov_b32_dpp v215, v45 row_shr:1 row_mask:0xf bank_mask:0xf
	v_mov_b32_dpp v216, v46 row_shr:1 row_mask:0xf bank_mask:0xf
	v_mov_b32_dpp v217, v47 row_shr:1 row_mask:0xf bank_mask:0xf
	v_mov_b32_dpp v218, v48 row_shr:1 row_mask:0xf bank_mask:0xf
	v_mov_b32_dpp v219, v49 row_shr:1 row_mask:0xf bank_mask:0xf
	v_cndmask_b32_e64 v213, v213, 0, vcc
	v_cndmask_b32_e64 v212, v212, 0, vcc
	v_cndmask_b32_e64 v215, v215, 0, vcc
	v_cndmask_b32_e64 v214, v214, 0, vcc
	v_cndmask_b32_e64 v219, v219, 0, vcc
	v_cndmask_b32_e64 v218, v218, 0, vcc
	v_cndmask_b32_e64 v217, v217, 0, vcc
	v_cndmask_b32_e64 v216, v216, 0, vcc
	v_pk_fma_f32 v[24:25], v[222:223], v[214:215], v[234:235]
	v_pk_fma_f32 v[22:23], v[220:221], v[212:213], v[232:233]
	v_pk_fma_f32 v[24:25], v[226:227], v[218:219], v[24:25]
	v_pk_fma_f32 v[22:23], v[224:225], v[216:217], v[22:23]
	v_pk_fma_f32 v[92:93], v[108:109], v[230:231], v[24:25]
	v_pk_fma_f32 v[90:91], v[106:107], v[228:229], v[22:23]
	v_pk_fma_f32 v[22:23], v[222:223], v[218:219], v[234:235]
	v_pk_fma_f32 v[24:25], v[220:221], v[216:217], v[232:233]
	v_pk_fma_f32 v[22:23], v[108:109], v[226:227], v[22:23]
	v_pk_fma_f32 v[24:25], v[106:107], v[224:225], v[24:25]
	v_cndmask_b32_e64 v35, v109, 0, s[4:5]
	v_cndmask_b32_e64 v34, v108, 0, s[4:5]
	v_cndmask_b32_e64 v37, v107, 0, s[4:5]
	v_cndmask_b32_e64 v36, v106, 0, s[4:5]
	v_pk_fma_f32 v[84:85], v[112:113], v[230:231], v[22:23]
	v_pk_fma_f32 v[82:83], v[110:111], v[228:229], v[24:25]
	v_cndmask_b32_e64 v23, v111, 0, s[4:5]
	v_cndmask_b32_e64 v22, v110, 0, s[4:5]
	v_cndmask_b32_e64 v25, v113, 0, s[4:5]
	v_cndmask_b32_e64 v24, v112, 0, s[4:5]
	v_pk_fma_f32 v[36:37], v[36:37], v[220:221], v[232:233]
	v_pk_fma_f32 v[34:35], v[34:35], v[222:223], v[234:235]
	v_pk_fma_f32 v[36:37], v[22:23], v[224:225], v[36:37]
	v_pk_fma_f32 v[34:35], v[24:25], v[226:227], v[34:35]
	v_pk_fma_f32 v[22:23], v[22:23], v[220:221], v[232:233]
	v_pk_fma_f32 v[24:25], v[24:25], v[222:223], v[234:235]
	v_pk_fma_f32 v[22:23], v[42:43], v[224:225], v[22:23]
	v_pk_fma_f32 v[24:25], v[44:45], v[226:227], v[24:25]
	v_pk_fma_f32 v[70:71], v[42:43], v[228:229], v[36:37]
	v_pk_fma_f32 v[72:73], v[44:45], v[230:231], v[34:35]
	v_pk_fma_f32 v[22:23], v[46:47], v[228:229], v[22:23]
	v_pk_fma_f32 v[24:25], v[48:49], v[230:231], v[24:25]
	s_waitcnt lgkmcnt(0)
	v_mov_b32_dpp v154, v26 row_shr:1 row_mask:0xf bank_mask:0xf
	v_mov_b32_dpp v155, v27 row_shr:1 row_mask:0xf bank_mask:0xf
	v_mov_b32_dpp v156, v28 row_shr:1 row_mask:0xf bank_mask:0xf
	v_mov_b32_dpp v157, v29 row_shr:1 row_mask:0xf bank_mask:0xf
	v_mov_b32_dpp v158, v38 row_shr:1 row_mask:0xf bank_mask:0xf
	v_mov_b32_dpp v159, v39 row_shr:1 row_mask:0xf bank_mask:0xf
	v_mov_b32_dpp v160, v40 row_shr:1 row_mask:0xf bank_mask:0xf
	v_mov_b32_dpp v161, v41 row_shr:1 row_mask:0xf bank_mask:0xf
	v_cndmask_b32_e64 v155, v155, 0, vcc
	v_cndmask_b32_e64 v154, v154, 0, vcc
	v_cndmask_b32_e64 v157, v157, 0, vcc
	v_cndmask_b32_e64 v156, v156, 0, vcc
	v_cndmask_b32_e64 v161, v161, 0, vcc
	v_cndmask_b32_e64 v160, v160, 0, vcc
	v_cndmask_b32_e64 v159, v159, 0, vcc
	v_cndmask_b32_e64 v158, v158, 0, vcc
	v_pk_fma_f32 v[36:37], v[164:165], v[156:157], v[178:179]
	v_pk_fma_f32 v[34:35], v[162:163], v[154:155], v[176:177]
	v_pk_fma_f32 v[36:37], v[170:171], v[160:161], v[36:37]
	v_pk_fma_f32 v[34:35], v[168:169], v[158:159], v[34:35]
	v_pk_fma_f32 v[96:97], v[100:101], v[174:175], v[36:37]
	v_pk_fma_f32 v[94:95], v[98:99], v[172:173], v[34:35]
	v_pk_fma_f32 v[34:35], v[164:165], v[160:161], v[178:179]
	v_pk_fma_f32 v[36:37], v[162:163], v[158:159], v[176:177]
	v_pk_fma_f32 v[34:35], v[100:101], v[170:171], v[34:35]
	v_pk_fma_f32 v[36:37], v[98:99], v[168:169], v[36:37]
	v_cndmask_b32_e64 v79, v101, 0, s[4:5]
	v_cndmask_b32_e64 v78, v100, 0, s[4:5]
	v_cndmask_b32_e64 v81, v99, 0, s[4:5]
	v_cndmask_b32_e64 v80, v98, 0, s[4:5]
	v_pk_fma_f32 v[88:89], v[104:105], v[174:175], v[34:35]
	v_pk_fma_f32 v[86:87], v[102:103], v[172:173], v[36:37]
	v_cndmask_b32_e64 v35, v103, 0, s[4:5]
	v_cndmask_b32_e64 v34, v102, 0, s[4:5]
	v_cndmask_b32_e64 v37, v105, 0, s[4:5]
	v_cndmask_b32_e64 v36, v104, 0, s[4:5]
	v_pk_fma_f32 v[80:81], v[80:81], v[162:163], v[176:177]
	v_pk_fma_f32 v[78:79], v[78:79], v[164:165], v[178:179]
	s_nop 0
	v_pk_fma_f32 v[152:153], v[36:37], v[170:171], v[78:79]
	v_pk_fma_f32 v[78:79], v[34:35], v[168:169], v[80:81]
	v_pk_fma_f32 v[34:35], v[34:35], v[162:163], v[176:177]
	v_pk_fma_f32 v[36:37], v[36:37], v[164:165], v[178:179]
	v_pk_fma_f32 v[34:35], v[26:27], v[168:169], v[34:35]
	v_pk_fma_f32 v[36:37], v[28:29], v[170:171], v[36:37]
	v_pk_fma_f32 v[78:79], v[26:27], v[172:173], v[78:79]
	v_pk_fma_f32 v[80:81], v[28:29], v[174:175], v[152:153]
	v_pk_fma_f32 v[34:35], v[38:39], v[172:173], v[34:35]
	v_pk_fma_f32 v[36:37], v[40:41], v[174:175], v[36:37]
	s_cbranch_execnz .LBB0_608
